# hand-written rwkv_prep phase (8-byte loads, 4 channels per lane, 16-lane DPP reductions, params in VGPRs, next-row prefetch)
# speedup vs baseline: 1.1024x; 1.0526x over previous
; __device__ __forceinline__ float bf2f(u16 h) { return __uint_as_float(((unsigned)h) << 16); }
; __device__ __forceinline__ float prevP(const Params& p, const u16* P, int row, int c) {
;   const int rp = row > 0 ? row - 1 : 0;
;   float v = bf2f(P[(size_t)rp * 2816 + 256 + c]);
;   const bool start = (row < NP) ? ((row & 2047) == 0) : (((row - NP) & 3) == 0);
;   if (start) v = (row < NP) ? 0.f : p.in[3][(size_t)((row - NP) >> 2) * 2560 + c];
;   return v;
; __device__ __forceinline__ void rwkv_prep_phase(const Params& p) {
;   const u16* P = (const u16*)(p.ws + O_P);
;   u16* APRE = (u16*)(p.ws + O_APRE);
;   u16* WPRE = (u16*)(p.ws + O_WPRE);
;   float* SC = (float*)(p.ws + O_BS);
;   const int lane = threadIdx.x & 63, wave = __builtin_amdgcn_readfirstlane(threadIdx.x >> 6);
;   for (int row = blockIdx.x * 8 + wave; row < MT; row += gridDim.x * 8) {
;     const u16* Pr = P + (size_t)row * 2816 + 256;
; #pragma unroll 12
;     for (int h = 0; h < 12; h++) {
;       const int ch = h * 64 + lane;
;       float pr = bf2f(Pr[ch]), pk = bf2f(Pr[768 + ch]);
;       float qr = prevP(p, P, row, ch), qk = prevP(p, P, row, 768 + ch);
;       float wl = p.in[12][ch] + bf2f(WPRE[(size_t)row * 768 + ch]);
;       float r = pr + (qr - pr) * p.in[11][ch], k = pk + (qk - pk) * p.in[11][768 + ch];
.LBB0_475:
	v_readlane_b32 s2, v254, 18
	v_readlane_b32 s3, v254, 19
	v_and_b32_e32 v96, 63, v128
	v_lshrrev_b32_e32 v97, 6, v128
	s_sub_u32 s2, s2, 0x160
	s_subb_u32 s3, s3, 0
	s_load_dwordx2 s[4:5], s[2:3], 0x18
	s_load_dwordx4 s[8:11], s[2:3], 0x58
	s_load_dwordx2 s[12:13], s[2:3], 0x70
	s_load_dwordx4 s[16:19], s[2:3], 0x88
	s_load_dwordx2 s[20:21], s[2:3], 0x98
	v_lshlrev_b32_e32 v129, 3, v96
	v_lshlrev_b32_e32 v130, 4, v96
	v_lshrrev_b32_e32 v131, 4, v96
	v_lshlrev_b32_e32 v131, 4, v131
	v_readfirstlane_b32 s22, v97
	v_readlane_b32 s23, v254, 0
	s_nop 3
	s_lshl_b32 s23, s23, 3
	s_add_u32 s23, s23, s22
	s_add_u32 s24, s96, 0x7108300
	s_addc_u32 s25, s97, 0
	s_add_u32 s26, s96, 0xd408100
	s_addc_u32 s27, s97, 0
	s_add_u32 s28, s96, 0x2f08100
	s_addc_u32 s29, s97, 0
	s_add_u32 s30, s96, 0x47c8100
	s_addc_u32 s31, s97, 0
	s_waitcnt lgkmcnt(0)
	s_add_u32 s14, s8, 0xc00
	s_addc_u32 s15, s9, 0
	global_load_dwordx4 v[140:143], v130, s[10:11] offset:0
	global_load_dwordx4 v[144:147], v130, s[10:11] offset:1024
	global_load_dwordx4 v[148:151], v130, s[10:11] offset:2048
	global_load_dwordx4 v[152:155], v130, s[8:9] offset:0
	global_load_dwordx4 v[156:159], v130, s[8:9] offset:1024
	global_load_dwordx4 v[160:163], v130, s[8:9] offset:2048
	global_load_dwordx4 v[164:167], v130, s[14:15] offset:0
	global_load_dwordx4 v[168:171], v130, s[14:15] offset:1024
	global_load_dwordx4 v[172:175], v130, s[14:15] offset:2048
	global_load_dwordx4 v[176:179], v130, s[12:13] offset:0
	global_load_dwordx4 v[180:183], v130, s[12:13] offset:1024
	global_load_dwordx4 v[184:187], v130, s[12:13] offset:2048
	global_load_dwordx4 v[188:191], v130, s[16:17] offset:0
	global_load_dwordx4 v[192:195], v130, s[16:17] offset:1024
	global_load_dwordx4 v[196:199], v130, s[16:17] offset:2048
	global_load_dwordx4 v[200:203], v130, s[18:19] offset:0
	global_load_dwordx4 v[204:207], v130, s[18:19] offset:1024
	global_load_dwordx4 v[208:211], v130, s[18:19] offset:2048
	global_load_dwordx4 v[212:215], v130, s[20:21] offset:0
	global_load_dwordx4 v[216:219], v130, s[20:21] offset:1024
	global_load_dwordx4 v[220:223], v130, s[20:21] offset:2048
	s_mov_b32 s2, 0x10001
	s_mov_b32 s3, 0x10001
	s_cmp_lt_u32 s23, 0x4200
	s_cbranch_scc0 .Lpp_done
	s_mul_i32 s33, s23, 0x1600
	s_add_u32 s78, s24, s33
	s_addc_u32 s79, s25, 0
	s_sub_u32 s34, s23, 1
	s_max_i32 s34, s34, 0
	s_mul_i32 s34, s34, 0x1600
	s_add_u32 s80, s24, s34
	s_addc_u32 s81, s25, 0
	s_mul_i32 s33, s23, 0x600
	s_add_u32 s82, s26, s33
	s_addc_u32 s83, s27, 0
	s_add_u32 s84, s28, s33
	s_addc_u32 s85, s29, 0
	global_load_dwordx2 v[0:1], v129, s[78:79] offset:0
	global_load_dwordx2 v[6:7], v129, s[78:79] offset:1536
	global_load_dwordx2 v[12:13], v129, s[80:81] offset:0
	global_load_dwordx2 v[18:19], v129, s[80:81] offset:1536
	global_load_dwordx2 v[24:25], v129, s[82:83] offset:0
	global_load_dwordx2 v[30:31], v129, s[84:85] offset:0
	global_load_dwordx2 v[2:3], v129, s[78:79] offset:512
	global_load_dwordx2 v[8:9], v129, s[78:79] offset:2048
	global_load_dwordx2 v[14:15], v129, s[80:81] offset:512
	global_load_dwordx2 v[20:21], v129, s[80:81] offset:2048
	global_load_dwordx2 v[26:27], v129, s[82:83] offset:512
	global_load_dwordx2 v[32:33], v129, s[84:85] offset:512
	global_load_dwordx2 v[4:5], v129, s[78:79] offset:1024
	global_load_dwordx2 v[10:11], v129, s[78:79] offset:2560
	global_load_dwordx2 v[16:17], v129, s[80:81] offset:1024
	global_load_dwordx2 v[22:23], v129, s[80:81] offset:2560
	global_load_dwordx2 v[28:29], v129, s[82:83] offset:1024
	global_load_dwordx2 v[34:35], v129, s[84:85] offset:1024
	s_mov_b32 s86, 0
	s_cmp_ge_u32 s23, 0x4000
	s_cbranch_scc1 .Lpp_smp_f
	s_and_b32 s33, s23, 0x7ff
	s_cmp_eq_u32 s33, 0
	s_cselect_b32 s86, 1, 0
	s_branch .Lpp_rs_f
.Lpp_smp_f:
	s_sub_u32 s33, s23, 0x4000
	s_and_b32 s34, s33, 3
	s_cmp_lg_u32 s34, 0
	s_cbranch_scc1 .Lpp_rs_f
	s_mov_b32 s86, 2
	s_lshr_b32 s33, s33, 2
	s_mul_i32 s33, s33, 0x2800
	s_add_u32 s88, s4, s33
	s_addc_u32 s89, s5, 0
	global_load_dwordx4 v[72:75], v130, s[88:89] offset:0
	global_load_dwordx4 v[76:79], v130, s[88:89] offset:1024
	global_load_dwordx4 v[80:83], v130, s[88:89] offset:2048
	s_add_u32 s88, s88, 0xc00
	s_addc_u32 s89, s89, 0
	global_load_dwordx4 v[84:87], v130, s[88:89] offset:0
	global_load_dwordx4 v[88:91], v130, s[88:89] offset:1024
	global_load_dwordx4 v[92:95], v130, s[88:89] offset:2048
.Lpp_rs_f:
.Lpp_loop:
	s_mov_b32 s87, s23
	s_mov_b32 s35, s86
	s_add_u32 s23, s23, 0x800
	s_cmp_lt_u32 s23, 0x4200
	s_cbranch_scc0 .Lpp_nonext_a
	s_mul_i32 s33, s87, 0x600
	s_add_u32 s76, s26, s33
	s_addc_u32 s77, s27, 0
	s_add_u32 s90, s28, s33
	s_addc_u32 s91, s29, 0
	s_mul_i32 s33, s87, 0xc0
	s_add_u32 s6, s30, s33
	s_addc_u32 s7, s31, 0
	s_mov_b32 s22, s35
	s_mul_i32 s33, s23, 0x1600
	s_add_u32 s78, s24, s33
	s_addc_u32 s79, s25, 0
	s_sub_u32 s34, s23, 1
	s_max_i32 s34, s34, 0
	s_mul_i32 s34, s34, 0x1600
	s_add_u32 s80, s24, s34
	s_addc_u32 s81, s25, 0
	s_mul_i32 s33, s23, 0x600
	s_add_u32 s82, s26, s33
	s_addc_u32 s83, s27, 0
	s_add_u32 s84, s28, s33
	s_addc_u32 s85, s29, 0
	global_load_dwordx2 v[36:37], v129, s[78:79] offset:0
	global_load_dwordx2 v[42:43], v129, s[78:79] offset:1536
	global_load_dwordx2 v[48:49], v129, s[80:81] offset:0
	global_load_dwordx2 v[54:55], v129, s[80:81] offset:1536
	global_load_dwordx2 v[60:61], v129, s[82:83] offset:0
	global_load_dwordx2 v[66:67], v129, s[84:85] offset:0
	global_load_dwordx2 v[38:39], v129, s[78:79] offset:512
	global_load_dwordx2 v[44:45], v129, s[78:79] offset:2048
	global_load_dwordx2 v[50:51], v129, s[80:81] offset:512
	global_load_dwordx2 v[56:57], v129, s[80:81] offset:2048
	global_load_dwordx2 v[62:63], v129, s[82:83] offset:512
	global_load_dwordx2 v[68:69], v129, s[84:85] offset:512
	global_load_dwordx2 v[40:41], v129, s[78:79] offset:1024
	global_load_dwordx2 v[46:47], v129, s[78:79] offset:2560
	global_load_dwordx2 v[52:53], v129, s[80:81] offset:1024
	global_load_dwordx2 v[58:59], v129, s[80:81] offset:2560
	global_load_dwordx2 v[64:65], v129, s[82:83] offset:1024
	global_load_dwordx2 v[70:71], v129, s[84:85] offset:1024
	s_mov_b32 s86, 0
	s_cmp_ge_u32 s23, 0x4000
	s_cbranch_scc1 .Lpp_smp_an
	s_and_b32 s33, s23, 0x7ff
	s_cmp_eq_u32 s33, 0
	s_cselect_b32 s86, 1, 0
	s_branch .Lpp_rs_an

; __device__ __forceinline__ float bf2f(u16 h) { return __uint_as_float(((unsigned)h) << 16); }
; __device__ __forceinline__ float frcp_(float x) { return __builtin_amdgcn_rcpf(x); }
; __device__ __forceinline__ float sigmoidf_(float x) { return frcp_(1.0f + __expf(-x)); }
; __device__ __forceinline__ void rwkv_prep_phase(const Params& p) {
;     ...
;       const int ch = h * 64 + lane;
;       float pr = bf2f(Pr[ch]), pk = bf2f(Pr[768 + ch]);
;       float qr = prevP(p, P, row, ch), qk = prevP(p, P, row, 768 + ch);
;       float wl = p.in[12][ch] + bf2f(WPRE[(size_t)row * 768 + ch]);
;       float r = pr + (qr - pr) * p.in[11][ch], k = pk + (qk - pk) * p.in[11][768 + ch];
;       float a = sigmoidf_(p.in[14][ch] + bf2f(APRE[(size_t)row * 768 + ch]));
;       a = bf2f(f2bf(a));
;       float omd = 1.0f - __expf(-0.6065306597126334f * sigmoidf_(wl));
;       float kkr = k * p.in[17][ch];
;       float n2 = wsum64(kkr * kkr);
;       float inv = frcp_(fmaxf(__builtin_amdgcn_sqrtf(n2), 1e-12f));
;       float kap = kkr * inv;
;       float kp = k * (1.0f + (a - 1.0f) * p.in[18][ch]);
;       float al = kap * a;
;       float ar = wsum64(al * r);
;       float kr = wsum64(kp * r);
;       float bsum = wsum64(r * kp * p.in[19][ch]);
;       APRE[(size_t)row * 768 + ch] = f2bf(a);
;       WPRE[(size_t)row * 768 + ch] = f2bf(omd);
;       if (lane == 0) *(float4*)(SC + ((size_t)row * 12 + h) * 4) = make_float4(ar, kr, bsum, inv);
.Lpp_rs_an:
	s_cmp_eq_u32 s86, 2
	s_cbranch_scc1 .Lpp_w24_a
	s_waitcnt vmcnt(18)
	s_branch .Lpp_go_a
.Lpp_w24_a:
	s_waitcnt vmcnt(24)
	s_branch .Lpp_go_a
.Lpp_nonext_a:
	s_mul_i32 s33, s87, 0x600
	s_add_u32 s76, s26, s33
	s_addc_u32 s77, s27, 0
	s_add_u32 s90, s28, s33
	s_addc_u32 s91, s29, 0
	s_mul_i32 s33, s87, 0xc0
	s_add_u32 s6, s30, s33
	s_addc_u32 s7, s31, 0
	s_mov_b32 s22, s35
	s_waitcnt vmcnt(0)
.Lpp_go_a:
	s_mov_b32 s35, s86
	s_mov_b32 s86, s22
	v_lshlrev_b32_e32 v96, 16, v0
	v_and_b32_e32 v97, 0xffff0000, v0
	v_lshlrev_b32_e32 v98, 16, v1
	v_and_b32_e32 v99, 0xffff0000, v1
	v_lshlrev_b32_e32 v100, 16, v6
	v_and_b32_e32 v101, 0xffff0000, v6
	v_lshlrev_b32_e32 v102, 16, v7
	v_and_b32_e32 v103, 0xffff0000, v7
	v_lshlrev_b32_e32 v104, 16, v12
	v_and_b32_e32 v105, 0xffff0000, v12
	v_lshlrev_b32_e32 v106, 16, v13
	v_and_b32_e32 v107, 0xffff0000, v13
	v_lshlrev_b32_e32 v108, 16, v18
	v_and_b32_e32 v109, 0xffff0000, v18
	v_lshlrev_b32_e32 v110, 16, v19
	v_and_b32_e32 v111, 0xffff0000, v19
	s_cmp_eq_u32 s86, 0
	s_cbranch_scc1 .Lpp_ns_ap0
	s_cmp_eq_u32 s86, 1
	s_cbranch_scc0 .Lpp_ss_ap0
	v_mov_b32_e32 v104, 0
	v_mov_b32_e32 v108, 0
	v_mov_b32_e32 v105, 0
	v_mov_b32_e32 v109, 0
	v_mov_b32_e32 v106, 0
	v_mov_b32_e32 v110, 0
	v_mov_b32_e32 v107, 0
	v_mov_b32_e32 v111, 0
	s_branch .Lpp_ns_ap0
.Lpp_ss_ap0:
	v_mov_b32_e32 v104, v72
	v_mov_b32_e32 v108, v84
	v_mov_b32_e32 v105, v73
	v_mov_b32_e32 v109, v85
	v_mov_b32_e32 v106, v74
	v_mov_b32_e32 v110, v86
	v_mov_b32_e32 v107, v75
	v_mov_b32_e32 v111, v87
.Lpp_ns_ap0:
	v_sub_f32_e32 v104, v104, v96
	v_sub_f32_e32 v108, v108, v100
	v_sub_f32_e32 v105, v105, v97
	v_sub_f32_e32 v109, v109, v101
	v_sub_f32_e32 v106, v106, v98
	v_sub_f32_e32 v110, v110, v102
	v_sub_f32_e32 v107, v107, v99
	v_sub_f32_e32 v111, v111, v103
	v_fmac_f32_e32 v96, v104, v152
	v_fmac_f32_e32 v100, v108, v164
	v_fmac_f32_e32 v97, v105, v153
	v_fmac_f32_e32 v101, v109, v165
	v_fmac_f32_e32 v98, v106, v154
	v_fmac_f32_e32 v102, v110, v166
	v_fmac_f32_e32 v99, v107, v155
	v_fmac_f32_e32 v103, v111, v167
	v_mul_f32_e32 v112, v100, v188
	v_mul_f32_e32 v113, v101, v189
	v_mul_f32_e32 v114, v102, v190
	v_mul_f32_e32 v115, v103, v191
	v_mul_f32_e32 v104, v112, v112
	v_fmac_f32_e32 v104, v113, v113
	v_fmac_f32_e32 v104, v114, v114
	v_fmac_f32_e32 v104, v115, v115
	v_lshlrev_b32_e32 v116, 16, v30
	v_and_b32_e32 v117, 0xffff0000, v30
	v_lshlrev_b32_e32 v118, 16, v31
	v_and_b32_e32 v119, 0xffff0000, v31
	v_lshlrev_b32_e32 v120, 16, v24
	v_and_b32_e32 v121, 0xffff0000, v24
	v_lshlrev_b32_e32 v122, 16, v25
	v_and_b32_e32 v123, 0xffff0000, v25
	v_add_f32_e32 v116, v176, v116
	v_add_f32_e32 v120, v140, v120
	v_add_f32_e32 v117, v177, v117
	v_add_f32_e32 v121, v141, v121
	v_add_f32_e32 v118, v178, v118
	v_add_f32_e32 v122, v142, v122
	v_add_f32_e32 v119, v179, v119
	v_add_f32_e32 v123, v143, v123
	v_mul_f32_e32 v116, 0xbfb8aa3b, v116
	v_mul_f32_e32 v120, 0xbfb8aa3b, v120
	v_mul_f32_e32 v117, 0xbfb8aa3b, v117
	v_mul_f32_e32 v121, 0xbfb8aa3b, v121
	v_mul_f32_e32 v118, 0xbfb8aa3b, v118
	v_mul_f32_e32 v122, 0xbfb8aa3b, v122
	v_mul_f32_e32 v119, 0xbfb8aa3b, v119
	v_mul_f32_e32 v123, 0xbfb8aa3b, v123
	v_exp_f32_e32 v116, v116
	v_exp_f32_e32 v117, v117
	v_exp_f32_e32 v118, v118
	v_exp_f32_e32 v119, v119
	v_exp_f32_e32 v120, v120
	v_exp_f32_e32 v121, v121
	v_exp_f32_e32 v122, v122
	v_exp_f32_e32 v123, v123
	v_add_f32_e32 v116, 1.0, v116
	v_add_f32_e32 v120, 1.0, v120
	v_add_f32_e32 v117, 1.0, v117
	v_add_f32_e32 v121, 1.0, v121
	v_add_f32_e32 v118, 1.0, v118
	v_add_f32_e32 v122, 1.0, v122
	v_add_f32_e32 v119, 1.0, v119
	v_add_f32_e32 v123, 1.0, v123
	v_rcp_f32_e32 v116, v116
	v_rcp_f32_e32 v117, v117
	v_rcp_f32_e32 v118, v118
	v_rcp_f32_e32 v119, v119
	v_rcp_f32_e32 v120, v120
	v_rcp_f32_e32 v121, v121
	v_rcp_f32_e32 v122, v122
	v_rcp_f32_e32 v123, v123
	v_add_f32_dpp v104, v104, v104 quad_perm:[1,0,3,2] row_mask:0xf bank_mask:0xf bound_ctrl:1
	v_cvt_pk_bf16_f32 v108, v116, v117
	v_cvt_pk_bf16_f32 v109, v118, v119
	v_add_f32_dpp v104, v104, v104 quad_perm:[2,3,0,1] row_mask:0xf bank_mask:0xf bound_ctrl:1
	v_mul_f32_e32 v120, 0xbf1b4598, v120
	v_mul_f32_e32 v121, 0xbf1b4598, v121
	v_mul_f32_e32 v122, 0xbf1b4598, v122
	v_mul_f32_e32 v123, 0xbf1b4598, v123
	v_mul_f32_e32 v120, 0x3fb8aa3b, v120
	v_mul_f32_e32 v121, 0x3fb8aa3b, v121
	v_mul_f32_e32 v122, 0x3fb8aa3b, v122
	v_mul_f32_e32 v123, 0x3fb8aa3b, v123
	v_add_f32_dpp v104, v104, v104 row_half_mirror row_mask:0xf bank_mask:0xf bound_ctrl:1
	v_exp_f32_e32 v120, v120
	v_exp_f32_e32 v121, v121
	v_exp_f32_e32 v122, v122
	v_exp_f32_e32 v123, v123
	v_lshlrev_b32_e32 v116, 16, v108
	v_and_b32_e32 v117, 0xffff0000, v108
	v_add_f32_dpp v104, v104, v104 row_mirror row_mask:0xf bank_mask:0xf bound_ctrl:1
	v_lshlrev_b32_e32 v118, 16, v109
	v_and_b32_e32 v119, 0xffff0000, v109
	global_store_dwordx2 v129, v[108:109], s[90:91] offset:0
	v_sub_f32_e32 v120, 1.0, v120
	v_sub_f32_e32 v121, 1.0, v121
	v_sub_f32_e32 v122, 1.0, v122
	v_sub_f32_e32 v123, 1.0, v123
	v_sqrt_f32_e32 v105, v104
	v_cvt_pk_bf16_f32 v124, v120, v121
	v_cvt_pk_bf16_f32 v125, v122, v123
	v_max_f32_e32 v105, 0x2b8cbccc, v105
	v_rcp_f32_e32 v105, v105
	global_store_dwordx2 v129, v[124:125], s[76:77] offset:0
	v_add_f32_e32 v120, -1.0, v116
	v_add_f32_e32 v121, -1.0, v117
	v_add_f32_e32 v122, -1.0, v118
	v_add_f32_e32 v123, -1.0, v119
	v_fma_f32 v120, v200, v120, 1.0
	v_fma_f32 v121, v201, v121, 1.0
	v_fma_f32 v122, v202, v122, 1.0
	v_fma_f32 v123, v203, v123, 1.0
	v_mul_f32_e32 v100, v100, v120
	v_mul_f32_e32 v101, v101, v121
	v_mul_f32_e32 v102, v102, v122
	v_mul_f32_e32 v103, v103, v123
	v_mul_f32_e32 v112, v112, v105
	v_mul_f32_e32 v113, v113, v105
; __device__ __forceinline__ float frcp_(float x) { return __builtin_amdgcn_rcpf(x); }
; __device__ __forceinline__ void rwkv_prep_phase(const Params& p) {
;     ...
;       float kkr = k * p.in[17][ch];
;       float n2 = wsum64(kkr * kkr);
;       float inv = frcp_(fmaxf(__builtin_amdgcn_sqrtf(n2), 1e-12f));
;       float kap = kkr * inv;
;       float kp = k * (1.0f + (a - 1.0f) * p.in[18][ch]);
;       float al = kap * a;
;       float ar = wsum64(al * r);
;       float kr = wsum64(kp * r);
;       float bsum = wsum64(r * kp * p.in[19][ch]);
;       APRE[(size_t)row * 768 + ch] = f2bf(a);
;       WPRE[(size_t)row * 768 + ch] = f2bf(omd);
;       if (lane == 0) *(float4*)(SC + ((size_t)row * 12 + h) * 4) = make_float4(ar, kr, bsum, inv);
	v_mul_f32_e32 v114, v114, v105
	v_mul_f32_e32 v115, v115, v105
	v_mul_f32_e32 v112, v112, v116
	v_mul_f32_e32 v113, v113, v117
	v_mul_f32_e32 v114, v114, v118
	v_mul_f32_e32 v115, v115, v119
	v_mul_f32_e32 v100, v96, v100
	v_mul_f32_e32 v101, v97, v101
	v_mul_f32_e32 v102, v98, v102
	v_mul_f32_e32 v103, v99, v103
	v_mul_f32_e32 v120, v96, v112
	v_mov_b32_e32 v121, v100
	v_mul_f32_e32 v122, v100, v212
	v_fmac_f32_e32 v120, v97, v113
	v_add_f32_e32 v121, v121, v101
	v_fmac_f32_e32 v122, v101, v213
	v_fmac_f32_e32 v120, v98, v114
	v_add_f32_e32 v121, v121, v102
	v_fmac_f32_e32 v122, v102, v214
	v_fmac_f32_e32 v120, v99, v115
	v_add_f32_e32 v121, v121, v103
	v_fmac_f32_e32 v122, v103, v215
	s_nop 1
	v_add_f32_dpp v120, v120, v120 quad_perm:[1,0,3,2] row_mask:0xf bank_mask:0xf bound_ctrl:1
	v_add_f32_dpp v121, v121, v121 quad_perm:[1,0,3,2] row_mask:0xf bank_mask:0xf bound_ctrl:1
	v_add_f32_dpp v122, v122, v122 quad_perm:[1,0,3,2] row_mask:0xf bank_mask:0xf bound_ctrl:1
	v_add_f32_dpp v120, v120, v120 quad_perm:[2,3,0,1] row_mask:0xf bank_mask:0xf bound_ctrl:1
	v_add_f32_dpp v121, v121, v121 quad_perm:[2,3,0,1] row_mask:0xf bank_mask:0xf bound_ctrl:1
	v_add_f32_dpp v122, v122, v122 quad_perm:[2,3,0,1] row_mask:0xf bank_mask:0xf bound_ctrl:1
	v_add_f32_dpp v120, v120, v120 row_half_mirror row_mask:0xf bank_mask:0xf bound_ctrl:1
	v_add_f32_dpp v121, v121, v121 row_half_mirror row_mask:0xf bank_mask:0xf bound_ctrl:1
	v_add_f32_dpp v122, v122, v122 row_half_mirror row_mask:0xf bank_mask:0xf bound_ctrl:1
	v_add_f32_dpp v120, v120, v120 row_mirror row_mask:0xf bank_mask:0xf bound_ctrl:1
	v_add_f32_dpp v121, v121, v121 row_mirror row_mask:0xf bank_mask:0xf bound_ctrl:1
	v_add_f32_dpp v122, v122, v122 row_mirror row_mask:0xf bank_mask:0xf bound_ctrl:1
	v_mov_b32_e32 v123, v105
	s_mov_b64 exec, s[2:3]
	global_store_dwordx4 v131, v[120:123], s[6:7] offset:0
	s_mov_b64 exec, -1
	v_lshlrev_b32_e32 v96, 16, v2
	v_and_b32_e32 v97, 0xffff0000, v2
	v_lshlrev_b32_e32 v98, 16, v3
	v_and_b32_e32 v99, 0xffff0000, v3
	v_lshlrev_b32_e32 v100, 16, v8
	v_and_b32_e32 v101, 0xffff0000, v8
	v_lshlrev_b32_e32 v102, 16, v9
	v_and_b32_e32 v103, 0xffff0000, v9
	v_lshlrev_b32_e32 v104, 16, v14
	v_and_b32_e32 v105, 0xffff0000, v14
	v_lshlrev_b32_e32 v106, 16, v15
	v_and_b32_e32 v107, 0xffff0000, v15
	v_lshlrev_b32_e32 v108, 16, v20
	v_and_b32_e32 v109, 0xffff0000, v20
	v_lshlrev_b32_e32 v110, 16, v21
	v_and_b32_e32 v111, 0xffff0000, v21
	s_cmp_eq_u32 s86, 0
	s_cbranch_scc1 .Lpp_ns_ap1
	s_cmp_eq_u32 s86, 1
	s_cbranch_scc0 .Lpp_ss_ap1
	v_mov_b32_e32 v104, 0
	v_mov_b32_e32 v108, 0
	v_mov_b32_e32 v105, 0
	v_mov_b32_e32 v109, 0
	v_mov_b32_e32 v106, 0
	v_mov_b32_e32 v110, 0
	v_mov_b32_e32 v107, 0
	v_mov_b32_e32 v111, 0
	s_branch .Lpp_ns_ap1
.Lpp_ss_ap1:
	v_mov_b32_e32 v104, v76
	v_mov_b32_e32 v108, v88
	v_mov_b32_e32 v105, v77
	v_mov_b32_e32 v109, v89
	v_mov_b32_e32 v106, v78
	v_mov_b32_e32 v110, v90
	v_mov_b32_e32 v107, v79
	v_mov_b32_e32 v111, v91
.Lpp_ns_ap1:
	v_sub_f32_e32 v104, v104, v96
	v_sub_f32_e32 v108, v108, v100
	v_sub_f32_e32 v105, v105, v97
	v_sub_f32_e32 v109, v109, v101
	v_sub_f32_e32 v106, v106, v98
	v_sub_f32_e32 v110, v110, v102
	v_sub_f32_e32 v107, v107, v99
	v_sub_f32_e32 v111, v111, v103
	v_fmac_f32_e32 v96, v104, v156
	v_fmac_f32_e32 v100, v108, v168
	v_fmac_f32_e32 v97, v105, v157
	v_fmac_f32_e32 v101, v109, v169
	v_fmac_f32_e32 v98, v106, v158
	v_fmac_f32_e32 v102, v110, v170
	v_fmac_f32_e32 v99, v107, v159
	v_fmac_f32_e32 v103, v111, v171
	v_mul_f32_e32 v112, v100, v192
	v_mul_f32_e32 v113, v101, v193
	v_mul_f32_e32 v114, v102, v194
	v_mul_f32_e32 v115, v103, v195
	v_mul_f32_e32 v104, v112, v112
	v_fmac_f32_e32 v104, v113, v113
	v_fmac_f32_e32 v104, v114, v114
	v_fmac_f32_e32 v104, v115, v115
	v_lshlrev_b32_e32 v116, 16, v32
	v_and_b32_e32 v117, 0xffff0000, v32
	v_lshlrev_b32_e32 v118, 16, v33
	v_and_b32_e32 v119, 0xffff0000, v33
	v_lshlrev_b32_e32 v120, 16, v26
	v_and_b32_e32 v121, 0xffff0000, v26
	v_lshlrev_b32_e32 v122, 16, v27
	v_and_b32_e32 v123, 0xffff0000, v27
	v_add_f32_e32 v116, v180, v116
	v_add_f32_e32 v120, v144, v120
	v_add_f32_e32 v117, v181, v117
	v_add_f32_e32 v121, v145, v121
	v_add_f32_e32 v118, v182, v118
	v_add_f32_e32 v122, v146, v122
	v_add_f32_e32 v119, v183, v119
	v_add_f32_e32 v123, v147, v123
	v_mul_f32_e32 v116, 0xbfb8aa3b, v116
	v_mul_f32_e32 v120, 0xbfb8aa3b, v120
	v_mul_f32_e32 v117, 0xbfb8aa3b, v117
	v_mul_f32_e32 v121, 0xbfb8aa3b, v121
	v_mul_f32_e32 v118, 0xbfb8aa3b, v118
	v_mul_f32_e32 v122, 0xbfb8aa3b, v122
	v_mul_f32_e32 v119, 0xbfb8aa3b, v119
	v_mul_f32_e32 v123, 0xbfb8aa3b, v123
	v_exp_f32_e32 v116, v116
	v_exp_f32_e32 v117, v117
	v_exp_f32_e32 v118, v118
	v_exp_f32_e32 v119, v119
	v_exp_f32_e32 v120, v120
	v_exp_f32_e32 v121, v121
	v_exp_f32_e32 v122, v122
	v_exp_f32_e32 v123, v123
	v_add_f32_e32 v116, 1.0, v116
	v_add_f32_e32 v120, 1.0, v120
	v_add_f32_e32 v117, 1.0, v117
	v_add_f32_e32 v121, 1.0, v121
	v_add_f32_e32 v118, 1.0, v118
	v_add_f32_e32 v122, 1.0, v122
	v_add_f32_e32 v119, 1.0, v119
	v_add_f32_e32 v123, 1.0, v123
	v_rcp_f32_e32 v116, v116
	v_rcp_f32_e32 v117, v117
	v_rcp_f32_e32 v118, v118
	v_rcp_f32_e32 v119, v119
	v_rcp_f32_e32 v120, v120
	v_rcp_f32_e32 v121, v121
	v_rcp_f32_e32 v122, v122
	v_rcp_f32_e32 v123, v123
	v_add_f32_dpp v104, v104, v104 quad_perm:[1,0,3,2] row_mask:0xf bank_mask:0xf bound_ctrl:1
	v_cvt_pk_bf16_f32 v108, v116, v117
	v_cvt_pk_bf16_f32 v109, v118, v119
	v_add_f32_dpp v104, v104, v104 quad_perm:[2,3,0,1] row_mask:0xf bank_mask:0xf bound_ctrl:1
	v_mul_f32_e32 v120, 0xbf1b4598, v120
	v_mul_f32_e32 v121, 0xbf1b4598, v121
	v_mul_f32_e32 v122, 0xbf1b4598, v122
	v_mul_f32_e32 v123, 0xbf1b4598, v123
; __device__ __forceinline__ float frcp_(float x) { return __builtin_amdgcn_rcpf(x); }
; __device__ __forceinline__ float sigmoidf_(float x) { return frcp_(1.0f + __expf(-x)); }
; __device__ __forceinline__ void rwkv_prep_phase(const Params& p) {
;     ...
;       float omd = 1.0f - __expf(-0.6065306597126334f * sigmoidf_(wl));
;       float kkr = k * p.in[17][ch];
;       float n2 = wsum64(kkr * kkr);
;       float inv = frcp_(fmaxf(__builtin_amdgcn_sqrtf(n2), 1e-12f));
;       float kap = kkr * inv;
;       float kp = k * (1.0f + (a - 1.0f) * p.in[18][ch]);
;       float al = kap * a;
;       float ar = wsum64(al * r);
;       float kr = wsum64(kp * r);
;       float bsum = wsum64(r * kp * p.in[19][ch]);
;       APRE[(size_t)row * 768 + ch] = f2bf(a);
;       WPRE[(size_t)row * 768 + ch] = f2bf(omd);
;       if (lane == 0) *(float4*)(SC + ((size_t)row * 12 + h) * 4) = make_float4(ar, kr, bsum, inv);
	v_mul_f32_e32 v120, 0x3fb8aa3b, v120
	v_mul_f32_e32 v121, 0x3fb8aa3b, v121
	v_mul_f32_e32 v122, 0x3fb8aa3b, v122
	v_mul_f32_e32 v123, 0x3fb8aa3b, v123
	v_add_f32_dpp v104, v104, v104 row_half_mirror row_mask:0xf bank_mask:0xf bound_ctrl:1
	v_exp_f32_e32 v120, v120
	v_exp_f32_e32 v121, v121
	v_exp_f32_e32 v122, v122
	v_exp_f32_e32 v123, v123
	v_lshlrev_b32_e32 v116, 16, v108
	v_and_b32_e32 v117, 0xffff0000, v108
	v_add_f32_dpp v104, v104, v104 row_mirror row_mask:0xf bank_mask:0xf bound_ctrl:1
	v_lshlrev_b32_e32 v118, 16, v109
	v_and_b32_e32 v119, 0xffff0000, v109
	global_store_dwordx2 v129, v[108:109], s[90:91] offset:512
	v_sub_f32_e32 v120, 1.0, v120
	v_sub_f32_e32 v121, 1.0, v121
	v_sub_f32_e32 v122, 1.0, v122
	v_sub_f32_e32 v123, 1.0, v123
	v_sqrt_f32_e32 v105, v104
	v_cvt_pk_bf16_f32 v124, v120, v121
	v_cvt_pk_bf16_f32 v125, v122, v123
	v_max_f32_e32 v105, 0x2b8cbccc, v105
	v_rcp_f32_e32 v105, v105
	global_store_dwordx2 v129, v[124:125], s[76:77] offset:512
	v_add_f32_e32 v120, -1.0, v116
	v_add_f32_e32 v121, -1.0, v117
	v_add_f32_e32 v122, -1.0, v118
	v_add_f32_e32 v123, -1.0, v119
	v_fma_f32 v120, v204, v120, 1.0
	v_fma_f32 v121, v205, v121, 1.0
	v_fma_f32 v122, v206, v122, 1.0
	v_fma_f32 v123, v207, v123, 1.0
	v_mul_f32_e32 v100, v100, v120
	v_mul_f32_e32 v101, v101, v121
	v_mul_f32_e32 v102, v102, v122
	v_mul_f32_e32 v103, v103, v123
	v_mul_f32_e32 v112, v112, v105
	v_mul_f32_e32 v113, v113, v105
	v_mul_f32_e32 v114, v114, v105
	v_mul_f32_e32 v115, v115, v105
	v_mul_f32_e32 v112, v112, v116
	v_mul_f32_e32 v113, v113, v117
	v_mul_f32_e32 v114, v114, v118
	v_mul_f32_e32 v115, v115, v119
	v_mul_f32_e32 v100, v96, v100
	v_mul_f32_e32 v101, v97, v101
	v_mul_f32_e32 v102, v98, v102
	v_mul_f32_e32 v103, v99, v103
	v_mul_f32_e32 v120, v96, v112
	v_mov_b32_e32 v121, v100
	v_mul_f32_e32 v122, v100, v216
	v_fmac_f32_e32 v120, v97, v113
	v_add_f32_e32 v121, v121, v101
	v_fmac_f32_e32 v122, v101, v217
	v_fmac_f32_e32 v120, v98, v114
	v_add_f32_e32 v121, v121, v102
	v_fmac_f32_e32 v122, v102, v218
	v_fmac_f32_e32 v120, v99, v115
	v_add_f32_e32 v121, v121, v103
	v_fmac_f32_e32 v122, v103, v219
	s_nop 1
	v_add_f32_dpp v120, v120, v120 quad_perm:[1,0,3,2] row_mask:0xf bank_mask:0xf bound_ctrl:1
	v_add_f32_dpp v121, v121, v121 quad_perm:[1,0,3,2] row_mask:0xf bank_mask:0xf bound_ctrl:1
	v_add_f32_dpp v122, v122, v122 quad_perm:[1,0,3,2] row_mask:0xf bank_mask:0xf bound_ctrl:1
	v_add_f32_dpp v120, v120, v120 quad_perm:[2,3,0,1] row_mask:0xf bank_mask:0xf bound_ctrl:1
	v_add_f32_dpp v121, v121, v121 quad_perm:[2,3,0,1] row_mask:0xf bank_mask:0xf bound_ctrl:1
	v_add_f32_dpp v122, v122, v122 quad_perm:[2,3,0,1] row_mask:0xf bank_mask:0xf bound_ctrl:1
	v_add_f32_dpp v120, v120, v120 row_half_mirror row_mask:0xf bank_mask:0xf bound_ctrl:1
	v_add_f32_dpp v121, v121, v121 row_half_mirror row_mask:0xf bank_mask:0xf bound_ctrl:1
	v_add_f32_dpp v122, v122, v122 row_half_mirror row_mask:0xf bank_mask:0xf bound_ctrl:1
	v_add_f32_dpp v120, v120, v120 row_mirror row_mask:0xf bank_mask:0xf bound_ctrl:1
	v_add_f32_dpp v121, v121, v121 row_mirror row_mask:0xf bank_mask:0xf bound_ctrl:1
	v_add_f32_dpp v122, v122, v122 row_mirror row_mask:0xf bank_mask:0xf bound_ctrl:1
	v_mov_b32_e32 v123, v105
	s_mov_b64 exec, s[2:3]
	global_store_dwordx4 v131, v[120:123], s[6:7] offset:64
	s_mov_b64 exec, -1
	v_lshlrev_b32_e32 v96, 16, v4
	v_and_b32_e32 v97, 0xffff0000, v4
	v_lshlrev_b32_e32 v98, 16, v5
	v_and_b32_e32 v99, 0xffff0000, v5
	v_lshlrev_b32_e32 v100, 16, v10
	v_and_b32_e32 v101, 0xffff0000, v10
	v_lshlrev_b32_e32 v102, 16, v11
	v_and_b32_e32 v103, 0xffff0000, v11
	v_lshlrev_b32_e32 v104, 16, v16
	v_and_b32_e32 v105, 0xffff0000, v16
	v_lshlrev_b32_e32 v106, 16, v17
	v_and_b32_e32 v107, 0xffff0000, v17
	v_lshlrev_b32_e32 v108, 16, v22
	v_and_b32_e32 v109, 0xffff0000, v22
	v_lshlrev_b32_e32 v110, 16, v23
	v_and_b32_e32 v111, 0xffff0000, v23
	s_cmp_eq_u32 s86, 0
	s_cbranch_scc1 .Lpp_ns_ap2
	s_cmp_eq_u32 s86, 1
	s_cbranch_scc0 .Lpp_ss_ap2
	v_mov_b32_e32 v104, 0
	v_mov_b32_e32 v108, 0
	v_mov_b32_e32 v105, 0
	v_mov_b32_e32 v109, 0
	v_mov_b32_e32 v106, 0
	v_mov_b32_e32 v110, 0
	v_mov_b32_e32 v107, 0
	v_mov_b32_e32 v111, 0
	s_branch .Lpp_ns_ap2
.Lpp_ss_ap2:
	v_mov_b32_e32 v104, v80
	v_mov_b32_e32 v108, v92
	v_mov_b32_e32 v105, v81
	v_mov_b32_e32 v109, v93
	v_mov_b32_e32 v106, v82
	v_mov_b32_e32 v110, v94
	v_mov_b32_e32 v107, v83
	v_mov_b32_e32 v111, v95
; __device__ __forceinline__ float bf2f(u16 h) { return __uint_as_float(((unsigned)h) << 16); }
; __device__ __forceinline__ float frcp_(float x) { return __builtin_amdgcn_rcpf(x); }
; __device__ __forceinline__ float sigmoidf_(float x) { return frcp_(1.0f + __expf(-x)); }
; __device__ __forceinline__ void rwkv_prep_phase(const Params& p) {
;     ...
;     for (int h = 0; h < 12; h++) {
;       const int ch = h * 64 + lane;
;       float pr = bf2f(Pr[ch]), pk = bf2f(Pr[768 + ch]);
;       float qr = prevP(p, P, row, ch), qk = prevP(p, P, row, 768 + ch);
;       float wl = p.in[12][ch] + bf2f(WPRE[(size_t)row * 768 + ch]);
;       float r = pr + (qr - pr) * p.in[11][ch], k = pk + (qk - pk) * p.in[11][768 + ch];
;       float a = sigmoidf_(p.in[14][ch] + bf2f(APRE[(size_t)row * 768 + ch]));
;       a = bf2f(f2bf(a));
;       float omd = 1.0f - __expf(-0.6065306597126334f * sigmoidf_(wl));
;       float kkr = k * p.in[17][ch];
;       float n2 = wsum64(kkr * kkr);
;       float inv = frcp_(fmaxf(__builtin_amdgcn_sqrtf(n2), 1e-12f));
;       float kap = kkr * inv;
;       float kp = k * (1.0f + (a - 1.0f) * p.in[18][ch]);
;       float al = kap * a;
;       float ar = wsum64(al * r);
;       float kr = wsum64(kp * r);
;       float bsum = wsum64(r * kp * p.in[19][ch]);
;       APRE[(size_t)row * 768 + ch] = f2bf(a);
;       WPRE[(size_t)row * 768 + ch] = f2bf(omd);
;       if (lane == 0) *(float4*)(SC + ((size_t)row * 12 + h) * 4) = make_float4(ar, kr, bsum, inv);
.Lpp_ns_ap2:
	v_sub_f32_e32 v104, v104, v96
	v_sub_f32_e32 v108, v108, v100
	v_sub_f32_e32 v105, v105, v97
	v_sub_f32_e32 v109, v109, v101
	v_sub_f32_e32 v106, v106, v98
	v_sub_f32_e32 v110, v110, v102
	v_sub_f32_e32 v107, v107, v99
	v_sub_f32_e32 v111, v111, v103
	v_fmac_f32_e32 v96, v104, v160
	v_fmac_f32_e32 v100, v108, v172
	v_fmac_f32_e32 v97, v105, v161
	v_fmac_f32_e32 v101, v109, v173
	v_fmac_f32_e32 v98, v106, v162
	v_fmac_f32_e32 v102, v110, v174
	v_fmac_f32_e32 v99, v107, v163
	v_fmac_f32_e32 v103, v111, v175
	v_mul_f32_e32 v112, v100, v196
	v_mul_f32_e32 v113, v101, v197
	v_mul_f32_e32 v114, v102, v198
	v_mul_f32_e32 v115, v103, v199
	v_mul_f32_e32 v104, v112, v112
	v_fmac_f32_e32 v104, v113, v113
	v_fmac_f32_e32 v104, v114, v114
	v_fmac_f32_e32 v104, v115, v115
	v_lshlrev_b32_e32 v116, 16, v34
	v_and_b32_e32 v117, 0xffff0000, v34
	v_lshlrev_b32_e32 v118, 16, v35
	v_and_b32_e32 v119, 0xffff0000, v35
	v_lshlrev_b32_e32 v120, 16, v28
	v_and_b32_e32 v121, 0xffff0000, v28
	v_lshlrev_b32_e32 v122, 16, v29
	v_and_b32_e32 v123, 0xffff0000, v29
	v_add_f32_e32 v116, v184, v116
	v_add_f32_e32 v120, v148, v120
	v_add_f32_e32 v117, v185, v117
	v_add_f32_e32 v121, v149, v121
	v_add_f32_e32 v118, v186, v118
	v_add_f32_e32 v122, v150, v122
	v_add_f32_e32 v119, v187, v119
	v_add_f32_e32 v123, v151, v123
	v_mul_f32_e32 v116, 0xbfb8aa3b, v116
	v_mul_f32_e32 v120, 0xbfb8aa3b, v120
	v_mul_f32_e32 v117, 0xbfb8aa3b, v117
	v_mul_f32_e32 v121, 0xbfb8aa3b, v121
	v_mul_f32_e32 v118, 0xbfb8aa3b, v118
	v_mul_f32_e32 v122, 0xbfb8aa3b, v122
	v_mul_f32_e32 v119, 0xbfb8aa3b, v119
	v_mul_f32_e32 v123, 0xbfb8aa3b, v123
	v_exp_f32_e32 v116, v116
	v_exp_f32_e32 v117, v117
	v_exp_f32_e32 v118, v118
	v_exp_f32_e32 v119, v119
	v_exp_f32_e32 v120, v120
	v_exp_f32_e32 v121, v121
	v_exp_f32_e32 v122, v122
	v_exp_f32_e32 v123, v123
	v_add_f32_e32 v116, 1.0, v116
	v_add_f32_e32 v120, 1.0, v120
	v_add_f32_e32 v117, 1.0, v117
	v_add_f32_e32 v121, 1.0, v121
	v_add_f32_e32 v118, 1.0, v118
	v_add_f32_e32 v122, 1.0, v122
	v_add_f32_e32 v119, 1.0, v119
	v_add_f32_e32 v123, 1.0, v123
	v_rcp_f32_e32 v116, v116
	v_rcp_f32_e32 v117, v117
	v_rcp_f32_e32 v118, v118
	v_rcp_f32_e32 v119, v119
	v_rcp_f32_e32 v120, v120
	v_rcp_f32_e32 v121, v121
	v_rcp_f32_e32 v122, v122
	v_rcp_f32_e32 v123, v123
	v_add_f32_dpp v104, v104, v104 quad_perm:[1,0,3,2] row_mask:0xf bank_mask:0xf bound_ctrl:1
	v_cvt_pk_bf16_f32 v108, v116, v117
	v_cvt_pk_bf16_f32 v109, v118, v119
	v_add_f32_dpp v104, v104, v104 quad_perm:[2,3,0,1] row_mask:0xf bank_mask:0xf bound_ctrl:1
	v_mul_f32_e32 v120, 0xbf1b4598, v120
	v_mul_f32_e32 v121, 0xbf1b4598, v121
	v_mul_f32_e32 v122, 0xbf1b4598, v122
	v_mul_f32_e32 v123, 0xbf1b4598, v123
	v_mul_f32_e32 v120, 0x3fb8aa3b, v120
	v_mul_f32_e32 v121, 0x3fb8aa3b, v121
	v_mul_f32_e32 v122, 0x3fb8aa3b, v122
	v_mul_f32_e32 v123, 0x3fb8aa3b, v123
	v_add_f32_dpp v104, v104, v104 row_half_mirror row_mask:0xf bank_mask:0xf bound_ctrl:1
	v_exp_f32_e32 v120, v120
	v_exp_f32_e32 v121, v121
	v_exp_f32_e32 v122, v122
	v_exp_f32_e32 v123, v123
	v_lshlrev_b32_e32 v116, 16, v108
	v_and_b32_e32 v117, 0xffff0000, v108
	v_add_f32_dpp v104, v104, v104 row_mirror row_mask:0xf bank_mask:0xf bound_ctrl:1
	v_lshlrev_b32_e32 v118, 16, v109
	v_and_b32_e32 v119, 0xffff0000, v109
	global_store_dwordx2 v129, v[108:109], s[90:91] offset:1024
	v_sub_f32_e32 v120, 1.0, v120
	v_sub_f32_e32 v121, 1.0, v121
	v_sub_f32_e32 v122, 1.0, v122
	v_sub_f32_e32 v123, 1.0, v123
	v_sqrt_f32_e32 v105, v104
	v_cvt_pk_bf16_f32 v124, v120, v121
	v_cvt_pk_bf16_f32 v125, v122, v123
	v_max_f32_e32 v105, 0x2b8cbccc, v105
	v_rcp_f32_e32 v105, v105
	global_store_dwordx2 v129, v[124:125], s[76:77] offset:1024
	v_add_f32_e32 v120, -1.0, v116
	v_add_f32_e32 v121, -1.0, v117
	v_add_f32_e32 v122, -1.0, v118
	v_add_f32_e32 v123, -1.0, v119
	v_fma_f32 v120, v208, v120, 1.0
	v_fma_f32 v121, v209, v121, 1.0
	v_fma_f32 v122, v210, v122, 1.0
	v_fma_f32 v123, v211, v123, 1.0
	v_mul_f32_e32 v100, v100, v120
	v_mul_f32_e32 v101, v101, v121
	v_mul_f32_e32 v102, v102, v122
	v_mul_f32_e32 v103, v103, v123
	v_mul_f32_e32 v112, v112, v105
	v_mul_f32_e32 v113, v113, v105
	v_mul_f32_e32 v114, v114, v105
	v_mul_f32_e32 v115, v115, v105
	v_mul_f32_e32 v112, v112, v116
	v_mul_f32_e32 v113, v113, v117
	v_mul_f32_e32 v114, v114, v118
	v_mul_f32_e32 v115, v115, v119
	v_mul_f32_e32 v100, v96, v100
	v_mul_f32_e32 v101, v97, v101
	v_mul_f32_e32 v102, v98, v102
	v_mul_f32_e32 v103, v99, v103
	v_mul_f32_e32 v120, v96, v112
	v_mov_b32_e32 v121, v100
	v_mul_f32_e32 v122, v100, v220
	v_fmac_f32_e32 v120, v97, v113
	v_add_f32_e32 v121, v121, v101
	v_fmac_f32_e32 v122, v101, v221
	v_fmac_f32_e32 v120, v98, v114
	v_add_f32_e32 v121, v121, v102
	v_fmac_f32_e32 v122, v102, v222
	v_fmac_f32_e32 v120, v99, v115
	v_add_f32_e32 v121, v121, v103
	v_fmac_f32_e32 v122, v103, v223
	s_nop 1
	v_add_f32_dpp v120, v120, v120 quad_perm:[1,0,3,2] row_mask:0xf bank_mask:0xf bound_ctrl:1
	v_add_f32_dpp v121, v121, v121 quad_perm:[1,0,3,2] row_mask:0xf bank_mask:0xf bound_ctrl:1
	v_add_f32_dpp v122, v122, v122 quad_perm:[1,0,3,2] row_mask:0xf bank_mask:0xf bound_ctrl:1
	v_add_f32_dpp v120, v120, v120 quad_perm:[2,3,0,1] row_mask:0xf bank_mask:0xf bound_ctrl:1
	v_add_f32_dpp v121, v121, v121 quad_perm:[2,3,0,1] row_mask:0xf bank_mask:0xf bound_ctrl:1
	v_add_f32_dpp v122, v122, v122 quad_perm:[2,3,0,1] row_mask:0xf bank_mask:0xf bound_ctrl:1
	v_add_f32_dpp v120, v120, v120 row_half_mirror row_mask:0xf bank_mask:0xf bound_ctrl:1
	v_add_f32_dpp v121, v121, v121 row_half_mirror row_mask:0xf bank_mask:0xf bound_ctrl:1
	v_add_f32_dpp v122, v122, v122 row_half_mirror row_mask:0xf bank_mask:0xf bound_ctrl:1
	v_add_f32_dpp v120, v120, v120 row_mirror row_mask:0xf bank_mask:0xf bound_ctrl:1
	v_add_f32_dpp v121, v121, v121 row_mirror row_mask:0xf bank_mask:0xf bound_ctrl:1
	v_add_f32_dpp v122, v122, v122 row_mirror row_mask:0xf bank_mask:0xf bound_ctrl:1
	v_mov_b32_e32 v123, v105
	s_mov_b64 exec, s[2:3]
	global_store_dwordx4 v131, v[120:123], s[6:7] offset:128
	s_mov_b64 exec, -1
	s_mov_b32 s86, s35
	s_cmp_lt_u32 s23, 0x4200
	s_cbranch_scc0 .Lpp_done
; __device__ __forceinline__ float bf2f(u16 h) { return __uint_as_float(((unsigned)h) << 16); }
; __device__ __forceinline__ void rwkv_prep_phase(const Params& p) {
;     ...
;   for (int row = blockIdx.x * 8 + wave; row < MT; row += gridDim.x * 8) {
;     const u16* Pr = P + (size_t)row * 2816 + 256;
; #pragma unroll 12
;     for (int h = 0; h < 12; h++) {
;       const int ch = h * 64 + lane;
;       float pr = bf2f(Pr[ch]), pk = bf2f(Pr[768 + ch]);
;       float qr = prevP(p, P, row, ch), qk = prevP(p, P, row, 768 + ch);
;       float wl = p.in[12][ch] + bf2f(WPRE[(size_t)row * 768 + ch]);
;       float r = pr + (qr - pr) * p.in[11][ch], k = pk + (qk - pk) * p.in[11][768 + ch];
	s_mov_b32 s87, s23
	s_mov_b32 s35, s86
	s_add_u32 s23, s23, 0x800
	s_cmp_lt_u32 s23, 0x4200
	s_cbranch_scc0 .Lpp_nonext_b
	s_mul_i32 s33, s87, 0x600
	s_add_u32 s76, s26, s33
	s_addc_u32 s77, s27, 0
	s_add_u32 s90, s28, s33
	s_addc_u32 s91, s29, 0
	s_mul_i32 s33, s87, 0xc0
	s_add_u32 s6, s30, s33
	s_addc_u32 s7, s31, 0
	s_mov_b32 s22, s35
	s_mul_i32 s33, s23, 0x1600
	s_add_u32 s78, s24, s33
	s_addc_u32 s79, s25, 0
	s_sub_u32 s34, s23, 1
	s_max_i32 s34, s34, 0
	s_mul_i32 s34, s34, 0x1600
	s_add_u32 s80, s24, s34
	s_addc_u32 s81, s25, 0
	s_mul_i32 s33, s23, 0x600
	s_add_u32 s82, s26, s33
	s_addc_u32 s83, s27, 0
	s_add_u32 s84, s28, s33
	s_addc_u32 s85, s29, 0
	global_load_dwordx2 v[0:1], v129, s[78:79] offset:0
	global_load_dwordx2 v[6:7], v129, s[78:79] offset:1536
	global_load_dwordx2 v[12:13], v129, s[80:81] offset:0
	global_load_dwordx2 v[18:19], v129, s[80:81] offset:1536
	global_load_dwordx2 v[24:25], v129, s[82:83] offset:0
	global_load_dwordx2 v[30:31], v129, s[84:85] offset:0
	global_load_dwordx2 v[2:3], v129, s[78:79] offset:512
	global_load_dwordx2 v[8:9], v129, s[78:79] offset:2048
	global_load_dwordx2 v[14:15], v129, s[80:81] offset:512
	global_load_dwordx2 v[20:21], v129, s[80:81] offset:2048
	global_load_dwordx2 v[26:27], v129, s[82:83] offset:512
	global_load_dwordx2 v[32:33], v129, s[84:85] offset:512
	global_load_dwordx2 v[4:5], v129, s[78:79] offset:1024
	global_load_dwordx2 v[10:11], v129, s[78:79] offset:2560
	global_load_dwordx2 v[16:17], v129, s[80:81] offset:1024
	global_load_dwordx2 v[22:23], v129, s[80:81] offset:2560
	global_load_dwordx2 v[28:29], v129, s[82:83] offset:1024
	global_load_dwordx2 v[34:35], v129, s[84:85] offset:1024
	s_mov_b32 s86, 0
	s_cmp_ge_u32 s23, 0x4000
	s_cbranch_scc1 .Lpp_smp_bn
	s_and_b32 s33, s23, 0x7ff
	s_cmp_eq_u32 s33, 0
	s_cselect_b32 s86, 1, 0
	s_branch .Lpp_rs_bn

; __device__ __forceinline__ float bf2f(u16 h) { return __uint_as_float(((unsigned)h) << 16); }
; __device__ __forceinline__ float prevP(const Params& p, const u16* P, int row, int c) {
;   const int rp = row > 0 ? row - 1 : 0;
;   float v = bf2f(P[(size_t)rp * 2816 + 256 + c]);
;   const bool start = (row < NP) ? ((row & 2047) == 0) : (((row - NP) & 3) == 0);
;   if (start) v = (row < NP) ? 0.f : p.in[3][(size_t)((row - NP) >> 2) * 2560 + c];
;   return v;
; __device__ __forceinline__ void rwkv_prep_phase(const Params& p) {
;     ...
;       float pr = bf2f(Pr[ch]), pk = bf2f(Pr[768 + ch]);
;       float qr = prevP(p, P, row, ch), qk = prevP(p, P, row, 768 + ch);
.Lpp_go_b:
	s_mov_b32 s35, s86
	s_mov_b32 s86, s22
	v_lshlrev_b32_e32 v96, 16, v36
	v_and_b32_e32 v97, 0xffff0000, v36
	v_lshlrev_b32_e32 v98, 16, v37
	v_and_b32_e32 v99, 0xffff0000, v37
	v_lshlrev_b32_e32 v100, 16, v42
	v_and_b32_e32 v101, 0xffff0000, v42
	v_lshlrev_b32_e32 v102, 16, v43
	v_and_b32_e32 v103, 0xffff0000, v43
	v_lshlrev_b32_e32 v104, 16, v48
	v_and_b32_e32 v105, 0xffff0000, v48
	v_lshlrev_b32_e32 v106, 16, v49
	v_and_b32_e32 v107, 0xffff0000, v49
	v_lshlrev_b32_e32 v108, 16, v54
	v_and_b32_e32 v109, 0xffff0000, v54
	v_lshlrev_b32_e32 v110, 16, v55
	v_and_b32_e32 v111, 0xffff0000, v55
	s_cmp_eq_u32 s86, 0
	s_cbranch_scc1 .Lpp_ns_bp0
	s_cmp_eq_u32 s86, 1
	s_cbranch_scc0 .Lpp_ss_bp0
	v_mov_b32_e32 v104, 0
	v_mov_b32_e32 v108, 0
	v_mov_b32_e32 v105, 0
	v_mov_b32_e32 v109, 0
	v_mov_b32_e32 v106, 0
	v_mov_b32_e32 v110, 0
	v_mov_b32_e32 v107, 0
	v_mov_b32_e32 v111, 0
	s_branch .Lpp_ns_bp0

; __device__ __forceinline__ float bf2f(u16 h) { return __uint_as_float(((unsigned)h) << 16); }
; __device__ __forceinline__ float frcp_(float x) { return __builtin_amdgcn_rcpf(x); }
; __device__ __forceinline__ float sigmoidf_(float x) { return frcp_(1.0f + __expf(-x)); }
; __device__ __forceinline__ void rwkv_prep_phase(const Params& p) {
;     ...
;     for (int h = 0; h < 12; h++) {
;       const int ch = h * 64 + lane;
;       float pr = bf2f(Pr[ch]), pk = bf2f(Pr[768 + ch]);
;       float qr = prevP(p, P, row, ch), qk = prevP(p, P, row, 768 + ch);
;       float wl = p.in[12][ch] + bf2f(WPRE[(size_t)row * 768 + ch]);
;       float r = pr + (qr - pr) * p.in[11][ch], k = pk + (qk - pk) * p.in[11][768 + ch];
;       float a = sigmoidf_(p.in[14][ch] + bf2f(APRE[(size_t)row * 768 + ch]));
;       a = bf2f(f2bf(a));
;       float omd = 1.0f - __expf(-0.6065306597126334f * sigmoidf_(wl));
;       float kkr = k * p.in[17][ch];
;       float n2 = wsum64(kkr * kkr);
;       float inv = frcp_(fmaxf(__builtin_amdgcn_sqrtf(n2), 1e-12f));
;       float kap = kkr * inv;
;       float kp = k * (1.0f + (a - 1.0f) * p.in[18][ch]);
;       float al = kap * a;
;       float ar = wsum64(al * r);
;       float kr = wsum64(kp * r);
;       float bsum = wsum64(r * kp * p.in[19][ch]);
;       APRE[(size_t)row * 768 + ch] = f2bf(a);
;       WPRE[(size_t)row * 768 + ch] = f2bf(omd);
;       if (lane == 0) *(float4*)(SC + ((size_t)row * 12 + h) * 4) = make_float4(ar, kr, bsum, inv);
.Lpp_ns_bp0:
	v_sub_f32_e32 v104, v104, v96
	v_sub_f32_e32 v108, v108, v100
	v_sub_f32_e32 v105, v105, v97
	v_sub_f32_e32 v109, v109, v101
	v_sub_f32_e32 v106, v106, v98
	v_sub_f32_e32 v110, v110, v102
	v_sub_f32_e32 v107, v107, v99
	v_sub_f32_e32 v111, v111, v103
	v_fmac_f32_e32 v96, v104, v152
	v_fmac_f32_e32 v100, v108, v164
	v_fmac_f32_e32 v97, v105, v153
	v_fmac_f32_e32 v101, v109, v165
	v_fmac_f32_e32 v98, v106, v154
	v_fmac_f32_e32 v102, v110, v166
	v_fmac_f32_e32 v99, v107, v155
	v_fmac_f32_e32 v103, v111, v167
	v_mul_f32_e32 v112, v100, v188
	v_mul_f32_e32 v113, v101, v189
	v_mul_f32_e32 v114, v102, v190
	v_mul_f32_e32 v115, v103, v191
	v_mul_f32_e32 v104, v112, v112
	v_fmac_f32_e32 v104, v113, v113
	v_fmac_f32_e32 v104, v114, v114
	v_fmac_f32_e32 v104, v115, v115
	v_lshlrev_b32_e32 v116, 16, v66
	v_and_b32_e32 v117, 0xffff0000, v66
	v_lshlrev_b32_e32 v118, 16, v67
	v_and_b32_e32 v119, 0xffff0000, v67
	v_lshlrev_b32_e32 v120, 16, v60
	v_and_b32_e32 v121, 0xffff0000, v60
	v_lshlrev_b32_e32 v122, 16, v61
	v_and_b32_e32 v123, 0xffff0000, v61
	v_add_f32_e32 v116, v176, v116
	v_add_f32_e32 v120, v140, v120
	v_add_f32_e32 v117, v177, v117
	v_add_f32_e32 v121, v141, v121
	v_add_f32_e32 v118, v178, v118
	v_add_f32_e32 v122, v142, v122
	v_add_f32_e32 v119, v179, v119
	v_add_f32_e32 v123, v143, v123
	v_mul_f32_e32 v116, 0xbfb8aa3b, v116
	v_mul_f32_e32 v120, 0xbfb8aa3b, v120
	v_mul_f32_e32 v117, 0xbfb8aa3b, v117
	v_mul_f32_e32 v121, 0xbfb8aa3b, v121
	v_mul_f32_e32 v118, 0xbfb8aa3b, v118
	v_mul_f32_e32 v122, 0xbfb8aa3b, v122
	v_mul_f32_e32 v119, 0xbfb8aa3b, v119
	v_mul_f32_e32 v123, 0xbfb8aa3b, v123
	v_exp_f32_e32 v116, v116
	v_exp_f32_e32 v117, v117
	v_exp_f32_e32 v118, v118
	v_exp_f32_e32 v119, v119
	v_exp_f32_e32 v120, v120
	v_exp_f32_e32 v121, v121
	v_exp_f32_e32 v122, v122
	v_exp_f32_e32 v123, v123
	v_add_f32_e32 v116, 1.0, v116
	v_add_f32_e32 v120, 1.0, v120
	v_add_f32_e32 v117, 1.0, v117
	v_add_f32_e32 v121, 1.0, v121
	v_add_f32_e32 v118, 1.0, v118
	v_add_f32_e32 v122, 1.0, v122
	v_add_f32_e32 v119, 1.0, v119
	v_add_f32_e32 v123, 1.0, v123
	v_rcp_f32_e32 v116, v116
	v_rcp_f32_e32 v117, v117
	v_rcp_f32_e32 v118, v118
	v_rcp_f32_e32 v119, v119
	v_rcp_f32_e32 v120, v120
	v_rcp_f32_e32 v121, v121
	v_rcp_f32_e32 v122, v122
	v_rcp_f32_e32 v123, v123
	v_add_f32_dpp v104, v104, v104 quad_perm:[1,0,3,2] row_mask:0xf bank_mask:0xf bound_ctrl:1
	v_cvt_pk_bf16_f32 v108, v116, v117
	v_cvt_pk_bf16_f32 v109, v118, v119
	v_add_f32_dpp v104, v104, v104 quad_perm:[2,3,0,1] row_mask:0xf bank_mask:0xf bound_ctrl:1
	v_mul_f32_e32 v120, 0xbf1b4598, v120
	v_mul_f32_e32 v121, 0xbf1b4598, v121
	v_mul_f32_e32 v122, 0xbf1b4598, v122
	v_mul_f32_e32 v123, 0xbf1b4598, v123
	v_mul_f32_e32 v120, 0x3fb8aa3b, v120
	v_mul_f32_e32 v121, 0x3fb8aa3b, v121
	v_mul_f32_e32 v122, 0x3fb8aa3b, v122
	v_mul_f32_e32 v123, 0x3fb8aa3b, v123
	v_add_f32_dpp v104, v104, v104 row_half_mirror row_mask:0xf bank_mask:0xf bound_ctrl:1
	v_exp_f32_e32 v120, v120
	v_exp_f32_e32 v121, v121
	v_exp_f32_e32 v122, v122
	v_exp_f32_e32 v123, v123
	v_lshlrev_b32_e32 v116, 16, v108
	v_and_b32_e32 v117, 0xffff0000, v108
	v_add_f32_dpp v104, v104, v104 row_mirror row_mask:0xf bank_mask:0xf bound_ctrl:1
	v_lshlrev_b32_e32 v118, 16, v109
	v_and_b32_e32 v119, 0xffff0000, v109
	global_store_dwordx2 v129, v[108:109], s[90:91] offset:0
	v_sub_f32_e32 v120, 1.0, v120
	v_sub_f32_e32 v121, 1.0, v121
	v_sub_f32_e32 v122, 1.0, v122
	v_sub_f32_e32 v123, 1.0, v123
	v_sqrt_f32_e32 v105, v104
	v_cvt_pk_bf16_f32 v124, v120, v121
	v_cvt_pk_bf16_f32 v125, v122, v123
	v_max_f32_e32 v105, 0x2b8cbccc, v105
	v_rcp_f32_e32 v105, v105
	global_store_dwordx2 v129, v[124:125], s[76:77] offset:0
	v_add_f32_e32 v120, -1.0, v116
	v_add_f32_e32 v121, -1.0, v117
	v_add_f32_e32 v122, -1.0, v118
	v_add_f32_e32 v123, -1.0, v119
	v_fma_f32 v120, v200, v120, 1.0
	v_fma_f32 v121, v201, v121, 1.0
	v_fma_f32 v122, v202, v122, 1.0
	v_fma_f32 v123, v203, v123, 1.0
	v_mul_f32_e32 v100, v100, v120
	v_mul_f32_e32 v101, v101, v121
	v_mul_f32_e32 v102, v102, v122
	v_mul_f32_e32 v103, v103, v123
	v_mul_f32_e32 v112, v112, v105
	v_mul_f32_e32 v113, v113, v105
	v_mul_f32_e32 v114, v114, v105
	v_mul_f32_e32 v115, v115, v105
	v_mul_f32_e32 v112, v112, v116
	v_mul_f32_e32 v113, v113, v117
	v_mul_f32_e32 v114, v114, v118
	v_mul_f32_e32 v115, v115, v119
	v_mul_f32_e32 v100, v96, v100
	v_mul_f32_e32 v101, v97, v101
	v_mul_f32_e32 v102, v98, v102
	v_mul_f32_e32 v103, v99, v103
	v_mul_f32_e32 v120, v96, v112
	v_mov_b32_e32 v121, v100
	v_mul_f32_e32 v122, v100, v212
	v_fmac_f32_e32 v120, v97, v113
	v_add_f32_e32 v121, v121, v101
	v_fmac_f32_e32 v122, v101, v213
	v_fmac_f32_e32 v120, v98, v114
	v_add_f32_e32 v121, v121, v102
	v_fmac_f32_e32 v122, v102, v214
	v_fmac_f32_e32 v120, v99, v115
	v_add_f32_e32 v121, v121, v103
	v_fmac_f32_e32 v122, v103, v215
	s_nop 1
	v_add_f32_dpp v120, v120, v120 quad_perm:[1,0,3,2] row_mask:0xf bank_mask:0xf bound_ctrl:1
	v_add_f32_dpp v121, v121, v121 quad_perm:[1,0,3,2] row_mask:0xf bank_mask:0xf bound_ctrl:1
	v_add_f32_dpp v122, v122, v122 quad_perm:[1,0,3,2] row_mask:0xf bank_mask:0xf bound_ctrl:1
	v_add_f32_dpp v120, v120, v120 quad_perm:[2,3,0,1] row_mask:0xf bank_mask:0xf bound_ctrl:1
	v_add_f32_dpp v121, v121, v121 quad_perm:[2,3,0,1] row_mask:0xf bank_mask:0xf bound_ctrl:1
	v_add_f32_dpp v122, v122, v122 quad_perm:[2,3,0,1] row_mask:0xf bank_mask:0xf bound_ctrl:1
	v_add_f32_dpp v120, v120, v120 row_half_mirror row_mask:0xf bank_mask:0xf bound_ctrl:1
	v_add_f32_dpp v121, v121, v121 row_half_mirror row_mask:0xf bank_mask:0xf bound_ctrl:1
	v_add_f32_dpp v122, v122, v122 row_half_mirror row_mask:0xf bank_mask:0xf bound_ctrl:1
	v_add_f32_dpp v120, v120, v120 row_mirror row_mask:0xf bank_mask:0xf bound_ctrl:1
	v_add_f32_dpp v121, v121, v121 row_mirror row_mask:0xf bank_mask:0xf bound_ctrl:1
	v_add_f32_dpp v122, v122, v122 row_mirror row_mask:0xf bank_mask:0xf bound_ctrl:1
	v_mov_b32_e32 v123, v105
	s_mov_b64 exec, s[2:3]
	global_store_dwordx4 v131, v[120:123], s[6:7] offset:0
	s_mov_b64 exec, -1
	v_lshlrev_b32_e32 v96, 16, v38
	v_and_b32_e32 v97, 0xffff0000, v38
	v_lshlrev_b32_e32 v98, 16, v39
	v_and_b32_e32 v99, 0xffff0000, v39
	v_lshlrev_b32_e32 v100, 16, v44
	v_and_b32_e32 v101, 0xffff0000, v44
	v_lshlrev_b32_e32 v102, 16, v45
	v_and_b32_e32 v103, 0xffff0000, v45
	v_lshlrev_b32_e32 v104, 16, v50
	v_and_b32_e32 v105, 0xffff0000, v50
	v_lshlrev_b32_e32 v106, 16, v51
	v_and_b32_e32 v107, 0xffff0000, v51
	v_lshlrev_b32_e32 v108, 16, v56
	v_and_b32_e32 v109, 0xffff0000, v56
	v_lshlrev_b32_e32 v110, 16, v57
	v_and_b32_e32 v111, 0xffff0000, v57
	s_cmp_eq_u32 s86, 0
	s_cbranch_scc1 .Lpp_ns_bp1
	s_cmp_eq_u32 s86, 1
	s_cbranch_scc0 .Lpp_ss_bp1
	v_mov_b32_e32 v104, 0
	v_mov_b32_e32 v108, 0
	v_mov_b32_e32 v105, 0
	v_mov_b32_e32 v109, 0
	v_mov_b32_e32 v106, 0
	v_mov_b32_e32 v110, 0
	v_mov_b32_e32 v107, 0
	v_mov_b32_e32 v111, 0
	s_branch .Lpp_ns_bp1

; __device__ __forceinline__ float bf2f(u16 h) { return __uint_as_float(((unsigned)h) << 16); }
; __device__ __forceinline__ float frcp_(float x) { return __builtin_amdgcn_rcpf(x); }
; __device__ __forceinline__ float sigmoidf_(float x) { return frcp_(1.0f + __expf(-x)); }
; __device__ __forceinline__ void rwkv_prep_phase(const Params& p) {
;     ...
;     for (int h = 0; h < 12; h++) {
;       const int ch = h * 64 + lane;
;       float pr = bf2f(Pr[ch]), pk = bf2f(Pr[768 + ch]);
;       float qr = prevP(p, P, row, ch), qk = prevP(p, P, row, 768 + ch);
;       float wl = p.in[12][ch] + bf2f(WPRE[(size_t)row * 768 + ch]);
;       float r = pr + (qr - pr) * p.in[11][ch], k = pk + (qk - pk) * p.in[11][768 + ch];
;       float a = sigmoidf_(p.in[14][ch] + bf2f(APRE[(size_t)row * 768 + ch]));
;       a = bf2f(f2bf(a));
;       float omd = 1.0f - __expf(-0.6065306597126334f * sigmoidf_(wl));
;       float kkr = k * p.in[17][ch];
;       float n2 = wsum64(kkr * kkr);
;       float inv = frcp_(fmaxf(__builtin_amdgcn_sqrtf(n2), 1e-12f));
;       float kap = kkr * inv;
;       float kp = k * (1.0f + (a - 1.0f) * p.in[18][ch]);
;       float al = kap * a;
;       float ar = wsum64(al * r);
;       float kr = wsum64(kp * r);
;       float bsum = wsum64(r * kp * p.in[19][ch]);
;       APRE[(size_t)row * 768 + ch] = f2bf(a);
;       WPRE[(size_t)row * 768 + ch] = f2bf(omd);
;       if (lane == 0) *(float4*)(SC + ((size_t)row * 12 + h) * 4) = make_float4(ar, kr, bsum, inv);
.Lpp_ns_bp1:
	v_sub_f32_e32 v104, v104, v96
	v_sub_f32_e32 v108, v108, v100
	v_sub_f32_e32 v105, v105, v97
	v_sub_f32_e32 v109, v109, v101
	v_sub_f32_e32 v106, v106, v98
	v_sub_f32_e32 v110, v110, v102
	v_sub_f32_e32 v107, v107, v99
	v_sub_f32_e32 v111, v111, v103
	v_fmac_f32_e32 v96, v104, v156
	v_fmac_f32_e32 v100, v108, v168
	v_fmac_f32_e32 v97, v105, v157
	v_fmac_f32_e32 v101, v109, v169
	v_fmac_f32_e32 v98, v106, v158
	v_fmac_f32_e32 v102, v110, v170
	v_fmac_f32_e32 v99, v107, v159
	v_fmac_f32_e32 v103, v111, v171
	v_mul_f32_e32 v112, v100, v192
	v_mul_f32_e32 v113, v101, v193
	v_mul_f32_e32 v114, v102, v194
	v_mul_f32_e32 v115, v103, v195
	v_mul_f32_e32 v104, v112, v112
	v_fmac_f32_e32 v104, v113, v113
	v_fmac_f32_e32 v104, v114, v114
	v_fmac_f32_e32 v104, v115, v115
	v_lshlrev_b32_e32 v116, 16, v68
	v_and_b32_e32 v117, 0xffff0000, v68
	v_lshlrev_b32_e32 v118, 16, v69
	v_and_b32_e32 v119, 0xffff0000, v69
	v_lshlrev_b32_e32 v120, 16, v62
	v_and_b32_e32 v121, 0xffff0000, v62
	v_lshlrev_b32_e32 v122, 16, v63
	v_and_b32_e32 v123, 0xffff0000, v63
	v_add_f32_e32 v116, v180, v116
	v_add_f32_e32 v120, v144, v120
	v_add_f32_e32 v117, v181, v117
	v_add_f32_e32 v121, v145, v121
	v_add_f32_e32 v118, v182, v118
	v_add_f32_e32 v122, v146, v122
	v_add_f32_e32 v119, v183, v119
	v_add_f32_e32 v123, v147, v123
	v_mul_f32_e32 v116, 0xbfb8aa3b, v116
	v_mul_f32_e32 v120, 0xbfb8aa3b, v120
	v_mul_f32_e32 v117, 0xbfb8aa3b, v117
	v_mul_f32_e32 v121, 0xbfb8aa3b, v121
	v_mul_f32_e32 v118, 0xbfb8aa3b, v118
	v_mul_f32_e32 v122, 0xbfb8aa3b, v122
	v_mul_f32_e32 v119, 0xbfb8aa3b, v119
	v_mul_f32_e32 v123, 0xbfb8aa3b, v123
	v_exp_f32_e32 v116, v116
	v_exp_f32_e32 v117, v117
	v_exp_f32_e32 v118, v118
	v_exp_f32_e32 v119, v119
	v_exp_f32_e32 v120, v120
	v_exp_f32_e32 v121, v121
	v_exp_f32_e32 v122, v122
	v_exp_f32_e32 v123, v123
	v_add_f32_e32 v116, 1.0, v116
	v_add_f32_e32 v120, 1.0, v120
	v_add_f32_e32 v117, 1.0, v117
	v_add_f32_e32 v121, 1.0, v121
	v_add_f32_e32 v118, 1.0, v118
	v_add_f32_e32 v122, 1.0, v122
	v_add_f32_e32 v119, 1.0, v119
	v_add_f32_e32 v123, 1.0, v123
	v_rcp_f32_e32 v116, v116
	v_rcp_f32_e32 v117, v117
	v_rcp_f32_e32 v118, v118
	v_rcp_f32_e32 v119, v119
	v_rcp_f32_e32 v120, v120
	v_rcp_f32_e32 v121, v121
	v_rcp_f32_e32 v122, v122
	v_rcp_f32_e32 v123, v123
	v_add_f32_dpp v104, v104, v104 quad_perm:[1,0,3,2] row_mask:0xf bank_mask:0xf bound_ctrl:1
	v_cvt_pk_bf16_f32 v108, v116, v117
	v_cvt_pk_bf16_f32 v109, v118, v119
	v_add_f32_dpp v104, v104, v104 quad_perm:[2,3,0,1] row_mask:0xf bank_mask:0xf bound_ctrl:1
	v_mul_f32_e32 v120, 0xbf1b4598, v120
	v_mul_f32_e32 v121, 0xbf1b4598, v121
	v_mul_f32_e32 v122, 0xbf1b4598, v122
	v_mul_f32_e32 v123, 0xbf1b4598, v123
	v_mul_f32_e32 v120, 0x3fb8aa3b, v120
	v_mul_f32_e32 v121, 0x3fb8aa3b, v121
	v_mul_f32_e32 v122, 0x3fb8aa3b, v122
	v_mul_f32_e32 v123, 0x3fb8aa3b, v123
	v_add_f32_dpp v104, v104, v104 row_half_mirror row_mask:0xf bank_mask:0xf bound_ctrl:1
	v_exp_f32_e32 v120, v120
	v_exp_f32_e32 v121, v121
	v_exp_f32_e32 v122, v122
	v_exp_f32_e32 v123, v123
	v_lshlrev_b32_e32 v116, 16, v108
	v_and_b32_e32 v117, 0xffff0000, v108
	v_add_f32_dpp v104, v104, v104 row_mirror row_mask:0xf bank_mask:0xf bound_ctrl:1
	v_lshlrev_b32_e32 v118, 16, v109
	v_and_b32_e32 v119, 0xffff0000, v109
	global_store_dwordx2 v129, v[108:109], s[90:91] offset:512
	v_sub_f32_e32 v120, 1.0, v120
	v_sub_f32_e32 v121, 1.0, v121
	v_sub_f32_e32 v122, 1.0, v122
	v_sub_f32_e32 v123, 1.0, v123
	v_sqrt_f32_e32 v105, v104
	v_cvt_pk_bf16_f32 v124, v120, v121
	v_cvt_pk_bf16_f32 v125, v122, v123
	v_max_f32_e32 v105, 0x2b8cbccc, v105
	v_rcp_f32_e32 v105, v105
	global_store_dwordx2 v129, v[124:125], s[76:77] offset:512
	v_add_f32_e32 v120, -1.0, v116
	v_add_f32_e32 v121, -1.0, v117
	v_add_f32_e32 v122, -1.0, v118
	v_add_f32_e32 v123, -1.0, v119
	v_fma_f32 v120, v204, v120, 1.0
	v_fma_f32 v121, v205, v121, 1.0
	v_fma_f32 v122, v206, v122, 1.0
	v_fma_f32 v123, v207, v123, 1.0
	v_mul_f32_e32 v100, v100, v120
	v_mul_f32_e32 v101, v101, v121
	v_mul_f32_e32 v102, v102, v122
	v_mul_f32_e32 v103, v103, v123
	v_mul_f32_e32 v112, v112, v105
	v_mul_f32_e32 v113, v113, v105
	v_mul_f32_e32 v114, v114, v105
	v_mul_f32_e32 v115, v115, v105
	v_mul_f32_e32 v112, v112, v116
	v_mul_f32_e32 v113, v113, v117
	v_mul_f32_e32 v114, v114, v118
	v_mul_f32_e32 v115, v115, v119
	v_mul_f32_e32 v100, v96, v100
	v_mul_f32_e32 v101, v97, v101
	v_mul_f32_e32 v102, v98, v102
	v_mul_f32_e32 v103, v99, v103
	v_mul_f32_e32 v120, v96, v112
	v_mov_b32_e32 v121, v100
	v_mul_f32_e32 v122, v100, v216
	v_fmac_f32_e32 v120, v97, v113
	v_add_f32_e32 v121, v121, v101
	v_fmac_f32_e32 v122, v101, v217
	v_fmac_f32_e32 v120, v98, v114
	v_add_f32_e32 v121, v121, v102
	v_fmac_f32_e32 v122, v102, v218
	v_fmac_f32_e32 v120, v99, v115
	v_add_f32_e32 v121, v121, v103
	v_fmac_f32_e32 v122, v103, v219
	s_nop 1
	v_add_f32_dpp v120, v120, v120 quad_perm:[1,0,3,2] row_mask:0xf bank_mask:0xf bound_ctrl:1
	v_add_f32_dpp v121, v121, v121 quad_perm:[1,0,3,2] row_mask:0xf bank_mask:0xf bound_ctrl:1
	v_add_f32_dpp v122, v122, v122 quad_perm:[1,0,3,2] row_mask:0xf bank_mask:0xf bound_ctrl:1
	v_add_f32_dpp v120, v120, v120 quad_perm:[2,3,0,1] row_mask:0xf bank_mask:0xf bound_ctrl:1
	v_add_f32_dpp v121, v121, v121 quad_perm:[2,3,0,1] row_mask:0xf bank_mask:0xf bound_ctrl:1
	v_add_f32_dpp v122, v122, v122 quad_perm:[2,3,0,1] row_mask:0xf bank_mask:0xf bound_ctrl:1
	v_add_f32_dpp v120, v120, v120 row_half_mirror row_mask:0xf bank_mask:0xf bound_ctrl:1
	v_add_f32_dpp v121, v121, v121 row_half_mirror row_mask:0xf bank_mask:0xf bound_ctrl:1
	v_add_f32_dpp v122, v122, v122 row_half_mirror row_mask:0xf bank_mask:0xf bound_ctrl:1
	v_add_f32_dpp v120, v120, v120 row_mirror row_mask:0xf bank_mask:0xf bound_ctrl:1
	v_add_f32_dpp v121, v121, v121 row_mirror row_mask:0xf bank_mask:0xf bound_ctrl:1
	v_add_f32_dpp v122, v122, v122 row_mirror row_mask:0xf bank_mask:0xf bound_ctrl:1
	v_mov_b32_e32 v123, v105
	s_mov_b64 exec, s[2:3]
	global_store_dwordx4 v131, v[120:123], s[6:7] offset:64
	s_mov_b64 exec, -1
	v_lshlrev_b32_e32 v96, 16, v40
	v_and_b32_e32 v97, 0xffff0000, v40
	v_lshlrev_b32_e32 v98, 16, v41
	v_and_b32_e32 v99, 0xffff0000, v41
	v_lshlrev_b32_e32 v100, 16, v46
	v_and_b32_e32 v101, 0xffff0000, v46
	v_lshlrev_b32_e32 v102, 16, v47
	v_and_b32_e32 v103, 0xffff0000, v47
	v_lshlrev_b32_e32 v104, 16, v52
	v_and_b32_e32 v105, 0xffff0000, v52
	v_lshlrev_b32_e32 v106, 16, v53
	v_and_b32_e32 v107, 0xffff0000, v53
	v_lshlrev_b32_e32 v108, 16, v58
	v_and_b32_e32 v109, 0xffff0000, v58
	v_lshlrev_b32_e32 v110, 16, v59
	v_and_b32_e32 v111, 0xffff0000, v59
	s_cmp_eq_u32 s86, 0
	s_cbranch_scc1 .Lpp_ns_bp2
	s_cmp_eq_u32 s86, 1
	s_cbranch_scc0 .Lpp_ss_bp2
	v_mov_b32_e32 v104, 0
	v_mov_b32_e32 v108, 0
	v_mov_b32_e32 v105, 0
	v_mov_b32_e32 v109, 0
	v_mov_b32_e32 v106, 0
	v_mov_b32_e32 v110, 0
	v_mov_b32_e32 v107, 0
	v_mov_b32_e32 v111, 0
	s_branch .Lpp_ns_bp2

; __device__ __forceinline__ float bf2f(u16 h) { return __uint_as_float(((unsigned)h) << 16); }
; __device__ __forceinline__ float frcp_(float x) { return __builtin_amdgcn_rcpf(x); }
; __device__ __forceinline__ float sigmoidf_(float x) { return frcp_(1.0f + __expf(-x)); }
; __device__ __forceinline__ void rwkv_prep_phase(const Params& p) {
;     ...
;   for (int row = blockIdx.x * 8 + wave; row < MT; row += gridDim.x * 8) {
;     const u16* Pr = P + (size_t)row * 2816 + 256;
; #pragma unroll 12
;     for (int h = 0; h < 12; h++) {
;       const int ch = h * 64 + lane;
;       float pr = bf2f(Pr[ch]), pk = bf2f(Pr[768 + ch]);
;       float qr = prevP(p, P, row, ch), qk = prevP(p, P, row, 768 + ch);
;       float wl = p.in[12][ch] + bf2f(WPRE[(size_t)row * 768 + ch]);
;       float r = pr + (qr - pr) * p.in[11][ch], k = pk + (qk - pk) * p.in[11][768 + ch];
;       float a = sigmoidf_(p.in[14][ch] + bf2f(APRE[(size_t)row * 768 + ch]));
;       a = bf2f(f2bf(a));
;       float omd = 1.0f - __expf(-0.6065306597126334f * sigmoidf_(wl));
;       float kkr = k * p.in[17][ch];
;       float n2 = wsum64(kkr * kkr);
;       float inv = frcp_(fmaxf(__builtin_amdgcn_sqrtf(n2), 1e-12f));
;       float kap = kkr * inv;
;       float kp = k * (1.0f + (a - 1.0f) * p.in[18][ch]);
;       float al = kap * a;
;       float ar = wsum64(al * r);
;       float kr = wsum64(kp * r);
;       float bsum = wsum64(r * kp * p.in[19][ch]);
;       APRE[(size_t)row * 768 + ch] = f2bf(a);
;       WPRE[(size_t)row * 768 + ch] = f2bf(omd);
;       if (lane == 0) *(float4*)(SC + ((size_t)row * 12 + h) * 4) = make_float4(ar, kr, bsum, inv);
;     }
;   }
.Lpp_ns_bp2:
	v_sub_f32_e32 v104, v104, v96
	v_sub_f32_e32 v108, v108, v100
	v_sub_f32_e32 v105, v105, v97
	v_sub_f32_e32 v109, v109, v101
	v_sub_f32_e32 v106, v106, v98
	v_sub_f32_e32 v110, v110, v102
	v_sub_f32_e32 v107, v107, v99
	v_sub_f32_e32 v111, v111, v103
	v_fmac_f32_e32 v96, v104, v160
	v_fmac_f32_e32 v100, v108, v172
	v_fmac_f32_e32 v97, v105, v161
	v_fmac_f32_e32 v101, v109, v173
	v_fmac_f32_e32 v98, v106, v162
	v_fmac_f32_e32 v102, v110, v174
	v_fmac_f32_e32 v99, v107, v163
	v_fmac_f32_e32 v103, v111, v175
	v_mul_f32_e32 v112, v100, v196
	v_mul_f32_e32 v113, v101, v197
	v_mul_f32_e32 v114, v102, v198
	v_mul_f32_e32 v115, v103, v199
	v_mul_f32_e32 v104, v112, v112
	v_fmac_f32_e32 v104, v113, v113
	v_fmac_f32_e32 v104, v114, v114
	v_fmac_f32_e32 v104, v115, v115
	v_lshlrev_b32_e32 v116, 16, v70
	v_and_b32_e32 v117, 0xffff0000, v70
	v_lshlrev_b32_e32 v118, 16, v71
	v_and_b32_e32 v119, 0xffff0000, v71
	v_lshlrev_b32_e32 v120, 16, v64
	v_and_b32_e32 v121, 0xffff0000, v64
	v_lshlrev_b32_e32 v122, 16, v65
	v_and_b32_e32 v123, 0xffff0000, v65
	v_add_f32_e32 v116, v184, v116
	v_add_f32_e32 v120, v148, v120
	v_add_f32_e32 v117, v185, v117
	v_add_f32_e32 v121, v149, v121
	v_add_f32_e32 v118, v186, v118
	v_add_f32_e32 v122, v150, v122
	v_add_f32_e32 v119, v187, v119
	v_add_f32_e32 v123, v151, v123
	v_mul_f32_e32 v116, 0xbfb8aa3b, v116
	v_mul_f32_e32 v120, 0xbfb8aa3b, v120
	v_mul_f32_e32 v117, 0xbfb8aa3b, v117
	v_mul_f32_e32 v121, 0xbfb8aa3b, v121
	v_mul_f32_e32 v118, 0xbfb8aa3b, v118
	v_mul_f32_e32 v122, 0xbfb8aa3b, v122
	v_mul_f32_e32 v119, 0xbfb8aa3b, v119
	v_mul_f32_e32 v123, 0xbfb8aa3b, v123
	v_exp_f32_e32 v116, v116
	v_exp_f32_e32 v117, v117
	v_exp_f32_e32 v118, v118
	v_exp_f32_e32 v119, v119
	v_exp_f32_e32 v120, v120
	v_exp_f32_e32 v121, v121
	v_exp_f32_e32 v122, v122
	v_exp_f32_e32 v123, v123
	v_add_f32_e32 v116, 1.0, v116
	v_add_f32_e32 v120, 1.0, v120
	v_add_f32_e32 v117, 1.0, v117
	v_add_f32_e32 v121, 1.0, v121
	v_add_f32_e32 v118, 1.0, v118
	v_add_f32_e32 v122, 1.0, v122
	v_add_f32_e32 v119, 1.0, v119
	v_add_f32_e32 v123, 1.0, v123
	v_rcp_f32_e32 v116, v116
	v_rcp_f32_e32 v117, v117
	v_rcp_f32_e32 v118, v118
	v_rcp_f32_e32 v119, v119
	v_rcp_f32_e32 v120, v120
	v_rcp_f32_e32 v121, v121
	v_rcp_f32_e32 v122, v122
	v_rcp_f32_e32 v123, v123
	v_add_f32_dpp v104, v104, v104 quad_perm:[1,0,3,2] row_mask:0xf bank_mask:0xf bound_ctrl:1
	v_cvt_pk_bf16_f32 v108, v116, v117
	v_cvt_pk_bf16_f32 v109, v118, v119
	v_add_f32_dpp v104, v104, v104 quad_perm:[2,3,0,1] row_mask:0xf bank_mask:0xf bound_ctrl:1
	v_mul_f32_e32 v120, 0xbf1b4598, v120
	v_mul_f32_e32 v121, 0xbf1b4598, v121
	v_mul_f32_e32 v122, 0xbf1b4598, v122
	v_mul_f32_e32 v123, 0xbf1b4598, v123
	v_mul_f32_e32 v120, 0x3fb8aa3b, v120
	v_mul_f32_e32 v121, 0x3fb8aa3b, v121
	v_mul_f32_e32 v122, 0x3fb8aa3b, v122
	v_mul_f32_e32 v123, 0x3fb8aa3b, v123
	v_add_f32_dpp v104, v104, v104 row_half_mirror row_mask:0xf bank_mask:0xf bound_ctrl:1
	v_exp_f32_e32 v120, v120
	v_exp_f32_e32 v121, v121
	v_exp_f32_e32 v122, v122
	v_exp_f32_e32 v123, v123
	v_lshlrev_b32_e32 v116, 16, v108
	v_and_b32_e32 v117, 0xffff0000, v108
	v_add_f32_dpp v104, v104, v104 row_mirror row_mask:0xf bank_mask:0xf bound_ctrl:1
	v_lshlrev_b32_e32 v118, 16, v109
	v_and_b32_e32 v119, 0xffff0000, v109
	global_store_dwordx2 v129, v[108:109], s[90:91] offset:1024
	v_sub_f32_e32 v120, 1.0, v120
	v_sub_f32_e32 v121, 1.0, v121
	v_sub_f32_e32 v122, 1.0, v122
	v_sub_f32_e32 v123, 1.0, v123
	v_sqrt_f32_e32 v105, v104
	v_cvt_pk_bf16_f32 v124, v120, v121
	v_cvt_pk_bf16_f32 v125, v122, v123
	v_max_f32_e32 v105, 0x2b8cbccc, v105
	v_rcp_f32_e32 v105, v105
	global_store_dwordx2 v129, v[124:125], s[76:77] offset:1024
	v_add_f32_e32 v120, -1.0, v116
	v_add_f32_e32 v121, -1.0, v117
	v_add_f32_e32 v122, -1.0, v118
	v_add_f32_e32 v123, -1.0, v119
	v_fma_f32 v120, v208, v120, 1.0
	v_fma_f32 v121, v209, v121, 1.0
	v_fma_f32 v122, v210, v122, 1.0
	v_fma_f32 v123, v211, v123, 1.0
	v_mul_f32_e32 v100, v100, v120
	v_mul_f32_e32 v101, v101, v121
	v_mul_f32_e32 v102, v102, v122
	v_mul_f32_e32 v103, v103, v123
	v_mul_f32_e32 v112, v112, v105
	v_mul_f32_e32 v113, v113, v105
	v_mul_f32_e32 v114, v114, v105
	v_mul_f32_e32 v115, v115, v105
	v_mul_f32_e32 v112, v112, v116
	v_mul_f32_e32 v113, v113, v117
	v_mul_f32_e32 v114, v114, v118
	v_mul_f32_e32 v115, v115, v119
	v_mul_f32_e32 v100, v96, v100
	v_mul_f32_e32 v101, v97, v101
	v_mul_f32_e32 v102, v98, v102
	v_mul_f32_e32 v103, v99, v103
	v_mul_f32_e32 v120, v96, v112
	v_mov_b32_e32 v121, v100
	v_mul_f32_e32 v122, v100, v220
	v_fmac_f32_e32 v120, v97, v113
	v_add_f32_e32 v121, v121, v101
	v_fmac_f32_e32 v122, v101, v221
	v_fmac_f32_e32 v120, v98, v114
	v_add_f32_e32 v121, v121, v102
	v_fmac_f32_e32 v122, v102, v222
	v_fmac_f32_e32 v120, v99, v115
	v_add_f32_e32 v121, v121, v103
	v_fmac_f32_e32 v122, v103, v223
	s_nop 1
	v_add_f32_dpp v120, v120, v120 quad_perm:[1,0,3,2] row_mask:0xf bank_mask:0xf bound_ctrl:1
	v_add_f32_dpp v121, v121, v121 quad_perm:[1,0,3,2] row_mask:0xf bank_mask:0xf bound_ctrl:1
	v_add_f32_dpp v122, v122, v122 quad_perm:[1,0,3,2] row_mask:0xf bank_mask:0xf bound_ctrl:1
	v_add_f32_dpp v120, v120, v120 quad_perm:[2,3,0,1] row_mask:0xf bank_mask:0xf bound_ctrl:1
	v_add_f32_dpp v121, v121, v121 quad_perm:[2,3,0,1] row_mask:0xf bank_mask:0xf bound_ctrl:1
	v_add_f32_dpp v122, v122, v122 quad_perm:[2,3,0,1] row_mask:0xf bank_mask:0xf bound_ctrl:1
	v_add_f32_dpp v120, v120, v120 row_half_mirror row_mask:0xf bank_mask:0xf bound_ctrl:1
	v_add_f32_dpp v121, v121, v121 row_half_mirror row_mask:0xf bank_mask:0xf bound_ctrl:1
	v_add_f32_dpp v122, v122, v122 row_half_mirror row_mask:0xf bank_mask:0xf bound_ctrl:1
	v_add_f32_dpp v120, v120, v120 row_mirror row_mask:0xf bank_mask:0xf bound_ctrl:1
	v_add_f32_dpp v121, v121, v121 row_mirror row_mask:0xf bank_mask:0xf bound_ctrl:1
	v_add_f32_dpp v122, v122, v122 row_mirror row_mask:0xf bank_mask:0xf bound_ctrl:1
	v_mov_b32_e32 v123, v105
	s_mov_b64 exec, s[2:3]
	global_store_dwordx4 v131, v[120:123], s[6:7] offset:128
	s_mov_b64 exec, -1
	s_mov_b32 s86, s35
	s_cmp_lt_u32 s23, 0x4200
	s_cbranch_scc1 .Lpp_loop
.Lpp_done:
	s_waitcnt vmcnt(0) lgkmcnt(0)
